# th5 plus first fragment reads of each FFN GEMM1 unit issued before the unit decode
# baseline (speedup 1.0000x reference)
.LBB0_253:
	v_add_u32_e32 v176, 0x10000, v191
	v_add_u32_e32 v188, 0x14000, v191
	ds_read_b128 v[148:151], v176
	ds_read_b128 v[152:155], v176 offset:1024
	ds_read_b128 v[172:175], v176 offset:2048
	ds_read_b128 v[176:179], v176 offset:3072
	ds_read_b128 v[180:183], v188
	ds_read_b128 v[184:187], v188 offset:1024
	ds_read_b128 v[196:199], v188 offset:2048
	ds_read_b128 v[200:203], v188 offset:3072
	ds_read_b128 v[204:207], v194
	ds_read_b128 v[212:215], v194 offset:1024
	ds_read_b128 v[216:219], v194 offset:2048
	ds_read_b128 v[220:223], v194 offset:3072
	ds_read_b128 v[224:227], v194 offset:4096
	ds_read_b128 v[228:231], v194 offset:5120
	ds_read_b128 v[232:235], v194 offset:6144
	ds_read_b128 v[236:239], v194 offset:7168
	s_add_i32 s46, s46, 1
	v_readlane_b32 s8, v254, 46
	v_readlane_b32 s15, v252, 2
	s_mul_i32 s8, s46, s8
	s_mul_hi_u32 s9, s46, s15
	s_add_i32 s9, s9, s8
	s_mul_i32 s8, s46, s15
	v_readlane_b32 s15, v252, 3
	s_add_u32 s18, s8, s15
	v_readlane_b32 s8, v252, 57
	s_addc_u32 s19, s9, s8
	v_mov_b64_e32 v[20:21], 0x580
	v_cmp_lt_i64_e64 s[36:37], s[18:19], v[20:21]
	v_mov_b64_e32 v[20:21], 0x57f
	v_cmp_gt_i64_e32 vcc, s[18:19], v[20:21]
	s_cbranch_vccnz .LBB0_255
	s_ashr_i32 s8, s18, 31
	s_lshr_b32 s8, s8, 29
	s_add_i32 s8, s18, s8
	s_ashr_i32 s9, s8, 3
	s_and_b32 s8, s8, -8
	s_sub_i32 s8, s18, s8
	s_cmp_lt_i32 s8, 0
	s_movk_i32 s14, 0xb1
	s_cselect_b32 s14, s14, 0xb0
	s_mul_i32 s8, s8, s14
	s_add_i32 s8, s8, s9
	s_mul_hi_i32 s9, s8, 0x2e8ba2e9
	s_lshr_b32 s14, s9, 31
	s_ashr_i32 s9, s9, 6
	s_add_i32 s9, s9, s14
	s_lshl_b32 s15, s9, 3
	s_sub_i32 s14, 32, s15
	s_min_i32 s16, s14, 8
	s_abs_i32 s14, s16
	v_cvt_f32_u32_e32 v20, s14
	s_sub_i32 s18, 0, s14
	s_mulk_i32 s9, 0x160
	s_sub_i32 s8, s8, s9
	v_rcp_iflag_f32_e32 v20, v20
	s_abs_i32 s9, s8
	s_xor_b32 s17, s8, s16
	s_ashr_i32 s17, s17, 31
	v_mul_f32_e32 v20, 0x4f7ffffe, v20
	v_cvt_u32_f32_e32 v20, v20
	s_nop 0
	v_readfirstlane_b32 s19, v20
	s_mul_i32 s18, s18, s19
	s_mul_hi_u32 s18, s19, s18
	s_add_i32 s19, s19, s18
	s_mul_hi_u32 s18, s9, s19
	s_mul_i32 s19, s18, s14
	s_sub_i32 s9, s9, s19
	s_add_i32 s20, s18, 1
	s_sub_i32 s19, s9, s14
	s_cmp_ge_u32 s9, s14
	s_cselect_b32 s18, s20, s18
	s_cselect_b32 s9, s19, s9
	s_add_i32 s19, s18, 1
	s_cmp_ge_u32 s9, s14
	s_cselect_b32 s9, s19, s18
	s_xor_b32 s9, s9, s17
	s_sub_i32 s14, s9, s17
	s_mul_i32 s9, s14, s16
	s_sub_i32 s8, s8, s9
	s_add_i32 s16, s15, s8
.LBB0_255:
	s_ashr_i32 s17, s16, 31
	s_lshl_b64 s[8:9], s[16:17], 20
	v_readlane_b32 s18, v254, 39
	v_readlane_b32 s19, v254, 40
	s_add_u32 s18, s18, s8
	s_addc_u32 s19, s19, s9
	s_and_b64 s[8:9], s[36:37], exec
	s_cselect_b32 s8, s19, s3
	s_cselect_b32 s9, s18, s2
	s_ashr_i32 s15, s14, 31
	s_lshl_b64 s[20:21], s[14:15], 20
	s_add_u32 s20, s29, s20
	s_addc_u32 s21, s38, s21
	s_and_b64 s[26:27], s[36:37], exec
	s_cselect_b32 s15, s21, s23
	s_cselect_b32 s17, s20, s22
	s_add_u32 s2, s2, 0x80800
	s_addc_u32 s3, s3, 0
	s_add_u32 s33, s22, 0x100
	s_addc_u32 s34, s23, 0
	s_mov_b32 s35, -2
	s_add_u32 s22, s2, 0xfff80800
	s_addc_u32 s23, s3, -1
	s_add_i32 s48, 0, 0x10000
	s_cmp_eq_u32 s35, 28
	s_cselect_b32 s27, s8, s23
	s_cselect_b32 s26, s9, s22
	s_cselect_b32 s23, s15, s34
	s_cselect_b32 s22, s17, s33
	s_add_i32 s50, 0, 0x14000
	s_add_i32 m0, s39, 0xc000
	global_load_lds_dwordx4 v168, s[2:3]
	s_add_i32 m0, s39, 0xe000
	s_nop 0
	global_load_lds_dwordx4 v170, s[2:3]
	s_waitcnt vmcnt(8)
	s_waitcnt lgkmcnt(0)
	s_setprio 1
	s_barrier
	v_mfma_f32_16x16x32_bf16 v[144:147], v[148:151], v[204:207], 0
	v_mfma_f32_16x16x32_bf16 v[136:139], v[172:175], v[204:207], 0
	v_mfma_f32_16x16x32_bf16 v[128:131], v[148:151], v[216:219], 0
	v_mfma_f32_16x16x32_bf16 v[120:123], v[172:175], v[216:219], 0
	v_mfma_f32_16x16x32_bf16 v[112:115], v[148:151], v[224:227], 0
	v_mfma_f32_16x16x32_bf16 v[104:107], v[172:175], v[224:227], 0
	v_mfma_f32_16x16x32_bf16 v[96:99], v[148:151], v[232:235], 0
	v_mfma_f32_16x16x32_bf16 v[88:91], v[172:175], v[232:235], 0
	v_mfma_f32_16x16x32_bf16 v[144:147], v[152:155], v[212:215], v[144:147]
	v_mfma_f32_16x16x32_bf16 v[136:139], v[176:179], v[212:215], v[136:139]
	v_mfma_f32_16x16x32_bf16 v[128:131], v[152:155], v[220:223], v[128:131]
	v_mfma_f32_16x16x32_bf16 v[120:123], v[176:179], v[220:223], v[120:123]
	v_mfma_f32_16x16x32_bf16 v[112:115], v[152:155], v[228:231], v[112:115]
	v_mfma_f32_16x16x32_bf16 v[104:107], v[176:179], v[228:231], v[104:107]
	v_mfma_f32_16x16x32_bf16 v[96:99], v[152:155], v[236:239], v[96:99]
	v_mfma_f32_16x16x32_bf16 v[88:91], v[176:179], v[236:239], v[88:91]
	v_mfma_f32_16x16x32_bf16 v[140:143], v[180:183], v[204:207], 0
	v_mfma_f32_16x16x32_bf16 v[132:135], v[196:199], v[204:207], 0
	v_mfma_f32_16x16x32_bf16 v[124:127], v[180:183], v[216:219], 0
	v_mfma_f32_16x16x32_bf16 v[116:119], v[196:199], v[216:219], 0
	v_mfma_f32_16x16x32_bf16 v[108:111], v[180:183], v[224:227], 0
	v_mfma_f32_16x16x32_bf16 v[100:103], v[196:199], v[224:227], 0
	v_mfma_f32_16x16x32_bf16 v[92:95], v[180:183], v[232:235], 0
	v_mfma_f32_16x16x32_bf16 v[84:87], v[196:199], v[232:235], 0
	v_mfma_f32_16x16x32_bf16 v[140:143], v[184:187], v[212:215], v[140:143]
	v_mfma_f32_16x16x32_bf16 v[132:135], v[200:203], v[212:215], v[132:135]
	v_mfma_f32_16x16x32_bf16 v[124:127], v[184:187], v[220:223], v[124:127]
	v_mfma_f32_16x16x32_bf16 v[116:119], v[200:203], v[220:223], v[116:119]
	v_mfma_f32_16x16x32_bf16 v[108:111], v[184:187], v[228:231], v[108:111]
	v_mfma_f32_16x16x32_bf16 v[100:103], v[200:203], v[228:231], v[100:103]
	v_mfma_f32_16x16x32_bf16 v[92:95], v[184:187], v[236:239], v[92:95]
	v_mfma_f32_16x16x32_bf16 v[84:87], v[200:203], v[236:239], v[84:87]
	s_barrier
	s_setprio 0
	s_add_i32 s48, s48, s28
	s_add_u32 s98, s22, 0x80
	s_addc_u32 s99, s23, 0
	s_add_u32 s100, s26, 0x800
	s_addc_u32 s101, s27, 0
	s_mov_b32 m0, s48
	ds_read_b128 v[204:207], v194 offset:16384
	ds_read_b128 v[212:215], v194 offset:17408
	ds_read_b128 v[216:219], v194 offset:18432
	ds_read_b128 v[220:223], v194 offset:19456
	ds_read_b128 v[224:227], v194 offset:20480
	ds_read_b128 v[228:231], v194 offset:21504
	ds_read_b128 v[232:235], v194 offset:22528
	ds_read_b128 v[236:239], v194 offset:23552
	global_load_lds_dwordx4 v2, s[22:23]
	s_add_i32 m0, s48, 0x2000
	s_add_u32 s48, s22, 0x80000
	s_addc_u32 s49, s23, 0
	s_add_i32 s50, s50, s28
	global_load_lds_dwordx4 v156, s[22:23]
	s_mov_b32 m0, s50
	s_nop 0
	global_load_lds_dwordx4 v2, s[48:49]
	s_add_i32 m0, s50, 0x2000
	s_nop 0
	global_load_lds_dwordx4 v156, s[48:49]
	s_mov_b32 m0, s39
	s_nop 0
	global_load_lds_dwordx4 v160, s[26:27]
	s_mov_b32 m0, s41
	s_nop 0
	global_load_lds_dwordx4 v158, s[26:27]
	s_waitcnt vmcnt(8)
	s_waitcnt lgkmcnt(0)
	s_setprio 1
	s_barrier
	v_mfma_f32_16x16x32_bf16 v[80:83], v[148:151], v[204:207], 0
	v_mfma_f32_16x16x32_bf16 v[72:75], v[172:175], v[204:207], 0
	v_mfma_f32_16x16x32_bf16 v[64:67], v[148:151], v[216:219], 0
	v_mfma_f32_16x16x32_bf16 v[56:59], v[172:175], v[216:219], 0
	v_mfma_f32_16x16x32_bf16 v[48:51], v[148:151], v[224:227], 0
	v_mfma_f32_16x16x32_bf16 v[40:43], v[172:175], v[224:227], 0
	v_mfma_f32_16x16x32_bf16 v[32:35], v[148:151], v[232:235], 0
	v_mfma_f32_16x16x32_bf16 v[24:27], v[172:175], v[232:235], 0
	v_mfma_f32_16x16x32_bf16 v[80:83], v[152:155], v[212:215], v[80:83]
	v_mfma_f32_16x16x32_bf16 v[72:75], v[176:179], v[212:215], v[72:75]
	v_mfma_f32_16x16x32_bf16 v[64:67], v[152:155], v[220:223], v[64:67]
	v_mfma_f32_16x16x32_bf16 v[56:59], v[176:179], v[220:223], v[56:59]
	v_mfma_f32_16x16x32_bf16 v[48:51], v[152:155], v[228:231], v[48:51]
	v_mfma_f32_16x16x32_bf16 v[40:43], v[176:179], v[228:231], v[40:43]
	v_mfma_f32_16x16x32_bf16 v[32:35], v[152:155], v[236:239], v[32:35]
	v_mfma_f32_16x16x32_bf16 v[24:27], v[176:179], v[236:239], v[24:27]
	v_mfma_f32_16x16x32_bf16 v[76:79], v[180:183], v[204:207], 0
	v_mfma_f32_16x16x32_bf16 v[68:71], v[196:199], v[204:207], 0
	v_mfma_f32_16x16x32_bf16 v[60:63], v[180:183], v[216:219], 0
	v_mfma_f32_16x16x32_bf16 v[52:55], v[196:199], v[216:219], 0
	v_mfma_f32_16x16x32_bf16 v[44:47], v[180:183], v[224:227], 0
	v_mfma_f32_16x16x32_bf16 v[36:39], v[196:199], v[224:227], 0
	v_mfma_f32_16x16x32_bf16 v[28:31], v[180:183], v[232:235], 0
	v_mfma_f32_16x16x32_bf16 v[20:23], v[196:199], v[232:235], 0
	v_mfma_f32_16x16x32_bf16 v[76:79], v[184:187], v[212:215], v[76:79]
	v_mfma_f32_16x16x32_bf16 v[68:71], v[200:203], v[212:215], v[68:71]
	v_mfma_f32_16x16x32_bf16 v[60:63], v[184:187], v[220:223], v[60:63]
	v_mfma_f32_16x16x32_bf16 v[52:55], v[200:203], v[220:223], v[52:55]
	v_mfma_f32_16x16x32_bf16 v[44:47], v[184:187], v[228:231], v[44:47]
	v_mfma_f32_16x16x32_bf16 v[36:39], v[200:203], v[228:231], v[36:39]
	v_mfma_f32_16x16x32_bf16 v[28:31], v[184:187], v[236:239], v[28:31]
	v_mfma_f32_16x16x32_bf16 v[20:23], v[200:203], v[236:239], v[20:23]
	s_barrier
	s_setprio 0
	s_add_i32 s48, 0, 0x18000
	s_add_i32 s49, 0, 0x1c000
	v_add_u32_e32 v176, s48, v191
	v_add_u32_e32 v195, s49, v191
	ds_read_b128 v[148:151], v176
	ds_read_b128 v[152:155], v176 offset:1024
	ds_read_b128 v[172:175], v176 offset:2048
	ds_read_b128 v[176:179], v176 offset:3072
	ds_read_b128 v[180:183], v195
	ds_read_b128 v[184:187], v195 offset:1024
	ds_read_b128 v[196:199], v195 offset:2048
	ds_read_b128 v[200:203], v195 offset:3072
	s_add_u32 s26, s26, 0x80000
	s_addc_u32 s27, s27, 0
	s_mov_b32 m0, s42
	ds_read_b128 v[204:207], v194 offset:32768
	ds_read_b128 v[212:215], v194 offset:33792
	ds_read_b128 v[216:219], v194 offset:34816
	ds_read_b128 v[220:223], v194 offset:35840
	ds_read_b128 v[224:227], v194 offset:36864
	ds_read_b128 v[228:231], v194 offset:37888
	ds_read_b128 v[232:235], v194 offset:38912
	ds_read_b128 v[236:239], v194 offset:39936
	global_load_lds_dwordx4 v160, s[26:27]
	s_mov_b32 m0, s43
	s_nop 0
	global_load_lds_dwordx4 v158, s[26:27]
	s_waitcnt vmcnt(8)
	s_waitcnt lgkmcnt(0)
	s_setprio 1
	s_barrier
	v_mfma_f32_16x16x32_bf16 v[144:147], v[148:151], v[204:207], v[144:147]
	v_mfma_f32_16x16x32_bf16 v[136:139], v[172:175], v[204:207], v[136:139]
	v_mfma_f32_16x16x32_bf16 v[128:131], v[148:151], v[216:219], v[128:131]
	v_mfma_f32_16x16x32_bf16 v[120:123], v[172:175], v[216:219], v[120:123]
	v_mfma_f32_16x16x32_bf16 v[112:115], v[148:151], v[224:227], v[112:115]
	v_mfma_f32_16x16x32_bf16 v[104:107], v[172:175], v[224:227], v[104:107]
	v_mfma_f32_16x16x32_bf16 v[96:99], v[148:151], v[232:235], v[96:99]
	v_mfma_f32_16x16x32_bf16 v[88:91], v[172:175], v[232:235], v[88:91]
	v_mfma_f32_16x16x32_bf16 v[144:147], v[152:155], v[212:215], v[144:147]
	v_mfma_f32_16x16x32_bf16 v[136:139], v[176:179], v[212:215], v[136:139]
	v_mfma_f32_16x16x32_bf16 v[128:131], v[152:155], v[220:223], v[128:131]
	v_mfma_f32_16x16x32_bf16 v[120:123], v[176:179], v[220:223], v[120:123]
	v_mfma_f32_16x16x32_bf16 v[112:115], v[152:155], v[228:231], v[112:115]
	v_mfma_f32_16x16x32_bf16 v[104:107], v[176:179], v[228:231], v[104:107]
	v_mfma_f32_16x16x32_bf16 v[96:99], v[152:155], v[236:239], v[96:99]
	v_mfma_f32_16x16x32_bf16 v[88:91], v[176:179], v[236:239], v[88:91]
	v_mfma_f32_16x16x32_bf16 v[140:143], v[180:183], v[204:207], v[140:143]
	v_mfma_f32_16x16x32_bf16 v[132:135], v[196:199], v[204:207], v[132:135]
	v_mfma_f32_16x16x32_bf16 v[124:127], v[180:183], v[216:219], v[124:127]
	v_mfma_f32_16x16x32_bf16 v[116:119], v[196:199], v[216:219], v[116:119]
	v_mfma_f32_16x16x32_bf16 v[108:111], v[180:183], v[224:227], v[108:111]
	v_mfma_f32_16x16x32_bf16 v[100:103], v[196:199], v[224:227], v[100:103]
	v_mfma_f32_16x16x32_bf16 v[92:95], v[180:183], v[232:235], v[92:95]
	v_mfma_f32_16x16x32_bf16 v[84:87], v[196:199], v[232:235], v[84:87]
	v_mfma_f32_16x16x32_bf16 v[140:143], v[184:187], v[212:215], v[140:143]
	v_mfma_f32_16x16x32_bf16 v[132:135], v[200:203], v[212:215], v[132:135]
	v_mfma_f32_16x16x32_bf16 v[124:127], v[184:187], v[220:223], v[124:127]
	v_mfma_f32_16x16x32_bf16 v[116:119], v[200:203], v[220:223], v[116:119]
	v_mfma_f32_16x16x32_bf16 v[108:111], v[184:187], v[228:231], v[108:111]
	v_mfma_f32_16x16x32_bf16 v[100:103], v[200:203], v[228:231], v[100:103]
	v_mfma_f32_16x16x32_bf16 v[92:95], v[184:187], v[236:239], v[92:95]
	v_mfma_f32_16x16x32_bf16 v[84:87], v[200:203], v[236:239], v[84:87]
	s_barrier
	s_setprio 0
	s_add_i32 s26, s48, s28
	s_mov_b32 m0, s26
	ds_read_b128 v[204:207], v194 offset:49152
	ds_read_b128 v[212:215], v194 offset:50176
	ds_read_b128 v[216:219], v194 offset:51200
	ds_read_b128 v[220:223], v194 offset:52224
	ds_read_b128 v[224:227], v194 offset:53248
	ds_read_b128 v[228:231], v194 offset:54272
	ds_read_b128 v[232:235], v194 offset:55296
	ds_read_b128 v[236:239], v194 offset:56320
	global_load_lds_dwordx4 v2, s[98:99]
	s_add_i32 m0, s26, 0x2000
	s_add_u32 s22, s22, 0x80080
	s_addc_u32 s23, s23, 0
	s_add_i32 s26, s49, s28
	global_load_lds_dwordx4 v156, s[98:99]
	s_mov_b32 m0, s26
	s_nop 0
	global_load_lds_dwordx4 v2, s[22:23]
	s_add_i32 m0, s26, 0x2000
	s_nop 0
	global_load_lds_dwordx4 v156, s[22:23]
	s_mov_b32 m0, s44
	s_nop 0
	global_load_lds_dwordx4 v160, s[100:101]
	s_mov_b32 m0, s45
	s_nop 0
	global_load_lds_dwordx4 v158, s[100:101]
	s_waitcnt vmcnt(8)
	s_waitcnt lgkmcnt(0)
	s_setprio 1
	s_barrier
	v_mfma_f32_16x16x32_bf16 v[80:83], v[148:151], v[204:207], v[80:83]
	v_mfma_f32_16x16x32_bf16 v[72:75], v[172:175], v[204:207], v[72:75]
	v_mfma_f32_16x16x32_bf16 v[64:67], v[148:151], v[216:219], v[64:67]
	v_mfma_f32_16x16x32_bf16 v[56:59], v[172:175], v[216:219], v[56:59]
	v_mfma_f32_16x16x32_bf16 v[48:51], v[148:151], v[224:227], v[48:51]
	v_mfma_f32_16x16x32_bf16 v[40:43], v[172:175], v[224:227], v[40:43]
	v_mfma_f32_16x16x32_bf16 v[32:35], v[148:151], v[232:235], v[32:35]
	v_mfma_f32_16x16x32_bf16 v[24:27], v[172:175], v[232:235], v[24:27]
	v_mfma_f32_16x16x32_bf16 v[80:83], v[152:155], v[212:215], v[80:83]
	v_mfma_f32_16x16x32_bf16 v[72:75], v[176:179], v[212:215], v[72:75]
	v_mfma_f32_16x16x32_bf16 v[64:67], v[152:155], v[220:223], v[64:67]
	v_mfma_f32_16x16x32_bf16 v[56:59], v[176:179], v[220:223], v[56:59]
	v_mfma_f32_16x16x32_bf16 v[48:51], v[152:155], v[228:231], v[48:51]
	v_mfma_f32_16x16x32_bf16 v[40:43], v[176:179], v[228:231], v[40:43]
	v_mfma_f32_16x16x32_bf16 v[32:35], v[152:155], v[236:239], v[32:35]
	v_mfma_f32_16x16x32_bf16 v[24:27], v[176:179], v[236:239], v[24:27]
	v_mfma_f32_16x16x32_bf16 v[76:79], v[180:183], v[204:207], v[76:79]
	v_mfma_f32_16x16x32_bf16 v[68:71], v[196:199], v[204:207], v[68:71]
	v_mfma_f32_16x16x32_bf16 v[60:63], v[180:183], v[216:219], v[60:63]
	v_mfma_f32_16x16x32_bf16 v[52:55], v[196:199], v[216:219], v[52:55]
	v_mfma_f32_16x16x32_bf16 v[44:47], v[180:183], v[224:227], v[44:47]
	v_mfma_f32_16x16x32_bf16 v[36:39], v[196:199], v[224:227], v[36:39]
	v_mfma_f32_16x16x32_bf16 v[28:31], v[180:183], v[232:235], v[28:31]
	v_mfma_f32_16x16x32_bf16 v[20:23], v[196:199], v[232:235], v[20:23]
	v_mfma_f32_16x16x32_bf16 v[76:79], v[184:187], v[212:215], v[76:79]
	v_mfma_f32_16x16x32_bf16 v[68:71], v[200:203], v[212:215], v[68:71]
	v_mfma_f32_16x16x32_bf16 v[60:63], v[184:187], v[220:223], v[60:63]
	v_mfma_f32_16x16x32_bf16 v[52:55], v[200:203], v[220:223], v[52:55]
	v_mfma_f32_16x16x32_bf16 v[44:47], v[184:187], v[228:231], v[44:47]
	v_mfma_f32_16x16x32_bf16 v[36:39], v[200:203], v[228:231], v[36:39]
	v_mfma_f32_16x16x32_bf16 v[28:31], v[184:187], v[236:239], v[28:31]
	v_mfma_f32_16x16x32_bf16 v[20:23], v[200:203], v[236:239], v[20:23]
	s_barrier
	s_setprio 0
	s_add_i32 s35, s35, 2
	s_add_u32 s2, s2, 0x1000
	s_addc_u32 s3, s3, 0
	s_add_u32 s33, s33, 0x100
	s_addc_u32 s34, s34, 0
	s_cmp_gt_u32 s35, 29
	s_cbranch_scc0 .LBB0_256
	s_branch .Lpeel_done_256
